# lever 4: one static s_setprio 1 for the younger half (waves 4-7) across the RWKV chunk loop (barrier-segmented MFMA+VALU stages); critical few-wave stages keep their own prio 3
# baseline (speedup 1.0000x reference)
; #define INP(k) (*(const float* const volatile __attribute__((address_space(4)))*)(ka + 8 * (k)))
; __device__ __forceinline__ void rwkv_chain(LAS unsigned char* lds, int cid, const bf16_t* P0, const float* mu, const float* w0, const float* w2, const float* a0, const float* a2, ...
;     ...
;     __syncthreads();
; __global__ void __launch_bounds__(512, 2) mk_fwd(Args args) {
;     ...
;         for (int cid = bx; cid < 256; cid += G)
;             rwkv_chain(lds, cid, P, INP(5), INP(6), INP(7), INP(8), INP(9), INP(11), INP(12), INP(13), H, SG, BONUS);
.LBB0_449:
	s_setprio 0
	v_readlane_b32 s64, v253, 24
	v_readlane_b32 s65, v253, 25
	s_waitcnt lgkmcnt(0)
	s_barrier
	s_load_dwordx2 s[96:97], s[64:65], 0x130
	v_readlane_b32 s72, v253, 36
	v_readlane_b32 s60, v253, 26
	v_readlane_b32 s94, v253, 32
	v_readlane_b32 s90, v253, 34
	s_waitcnt lgkmcnt(0)
	s_add_i32 s86, s86, s96
	s_cmpk_gt_i32 s86, 0xff
	v_readlane_b32 s73, v253, 37
	v_readlane_b32 s61, v253, 27
	v_readlane_b32 s57, v253, 52
	v_readlane_b32 s63, v253, 54
	v_readlane_b32 s95, v253, 33
	v_readlane_b32 s91, v253, 35
	s_cbranch_scc1 .LBB0_601

; #define LAS __attribute__((address_space(3)))
; __device__ __forceinline__ unsigned pk2(float lo, float hi) { const f32x2 v = {lo, hi}; return __builtin_bit_cast(unsigned, __builtin_convertvector(v, bf16x2_t)); }
; __device__ __forceinline__ unsigned f2bf(float f) { return pk2(f, 0.f) & 0xffffu; }
; __device__ __forceinline__ f32x4 mfma16(bf16x8 bfrag, bf16x8 afrag, f32x4 acc) { return __builtin_amdgcn_mfma_f32_16x16x32_bf16(bfrag, afrag, acc, 0, 0, 0); }
; __device__ __forceinline__ void rwkv_chain(LAS unsigned char* lds, int cid, const bf16_t* P0, const float* mu, const float* w0, const float* w2, const float* a0, const float* a2, ...
;     ...
;     for (int cc = 0; cc < 128; ++cc) {
;         const int t0 = dir ? (127 - cc) * 32 : cc * 32;
;         { RW_IDS
;         { const int tok = tid >> 4, c4 = (tid & 15) * 4;
; #pragma unroll
;         for (int i = 0; i < 5; ++i) {
;             const f32x4 mu4 = *(const LAS f32x4*)(cst + (5 + i) * 64 + c4);
;     ...
;         { RW_IDS const bf16x8 uf = ldsfrag(Ub, 40, vt * 16, 0, fr, fq);
;           oacc = mfma16(ldsfrag(MbrT, 40, tt2 * 16, 0, fr, fq), uf, oacc);
; #pragma unroll
;           for (int e = 0; e < 4; ++e) { const int sidx = tt2 * 16 + fq * 4 + e, tok = dir ? 31 - sidx : sidx;
;               ORW[(size_t)dir * T * 512 + ((size_t)b * SEQ + t0 + tok) * 512 + h * 64 + vt * 16 + fr] = (bf16_t)f2bf(oacc[e]); }
; #pragma unroll
;           for (int n2 = 0; n2 < 2; ++n2) { const int kt = tt2 * 2 + n2; st[n2] = mfma16(ldsfrag(BtT, 40, kt * 16, 0, fr, fq), uf, st[n2]);
;               const f32x4 gl = *(const LAS f32x4*)(gL + kt * 16 + fq * 4); st[n2] = st[n2] * gl;
;               u32x2 o; o.x = pk2(st[n2][0], st[n2][1]); o.y = pk2(st[n2][2], st[n2][3]); *(LAS u32x2*)(S0b + (vt * 16 + fr) * 72 + kt * 16 + fq * 4) = o; } }
.LBB0_486:
	s_lshl_b64 s[40:41], s[12:13], 12
	s_lshl_b64 s[2:3], s[38:39], 1
	s_add_u32 s42, s57, s2
	s_addc_u32 s43, s63, s3
	s_lshl_b32 s1, s1, 2
	v_readlane_b32 s2, v253, 30
	v_readlane_b32 s3, v253, 31
	s_add_u32 s44, s2, s1
	s_addc_u32 s45, s3, 0
	s_and_b64 s[2:3], s[10:11], exec
	s_cselect_b32 s90, 1, -1
	s_lshl_b32 s1, s87, 26
	v_readlane_b32 s2, v253, 21
	v_readlane_b32 s3, v253, 22
	s_add_u32 s1, s2, s1
	s_addc_u32 s2, s3, 0
	s_lshl_b32 s0, s0, 1
	s_add_u32 s91, s1, s0
	s_addc_u32 s92, s2, 0
	s_and_b64 s[0:1], s[10:11], exec
	s_movk_i32 s8, 0x1e00
	s_movk_i32 s9, 0x1d00
	s_movk_i32 s12, 0x1b00
	s_movk_i32 s13, 0x1a00
	s_movk_i32 s14, 0x1900
	s_movk_i32 s15, 0x1800
	s_movk_i32 s16, 0x1700
	s_movk_i32 s17, 0x1600
	s_movk_i32 s46, 0x1500
	s_movk_i32 s47, 0x1400
	s_movk_i32 s48, 0x1300
	s_movk_i32 s49, 0x1200
	s_movk_i32 s5, 0x1100
	s_cselect_b32 s93, 0x1f00, 0
	s_cselect_b32 s94, s8, 0x100
	s_cselect_b32 s95, s9, 0x200
	s_cselect_b32 s96, s62, 0x300
	s_cselect_b32 s97, s12, 0x400
	s_cselect_b32 s22, s13, 0x500
	s_cselect_b32 s23, s14, 0x600
	s_cselect_b32 s18, s15, 0x700
	s_cselect_b32 s19, s16, 0x800
	s_cselect_b32 s2, s17, 0x900
	s_cselect_b32 s3, s46, 0xa00
	s_cselect_b32 s56, s47, 0xb00
	s_cselect_b32 s57, s48, 0xc00
	s_cselect_b32 s0, s49, 0xd00
	s_cselect_b32 s1, s5, 0xe00
	s_lshl_b32 s4, s87, 8
	s_and_b64 s[6:7], s[10:11], exec
	s_cselect_b32 s5, 0xe00, s5
	s_cselect_b32 s60, 0xd00, s49
	s_cselect_b32 s61, 0xc00, s48
	s_cselect_b32 s63, 0xb00, s47
	s_cselect_b32 s64, 0xa00, s46
	s_cselect_b32 s65, 0x900, s17
	s_cselect_b32 s66, 0x800, s16
	s_cselect_b32 s67, 0x700, s15
	s_cselect_b32 s68, 0x600, s14
	s_cselect_b32 s69, 0x500, s13
	s_cselect_b32 s70, 0x400, s12
	s_cselect_b32 s71, 0x300, s62
	s_cselect_b32 s72, 0x200, s9
	s_cselect_b32 s73, 0x100, s8
	s_cselect_b32 s8, 0, 0x1f00
	s_sub_i32 s9, 0, s4
	s_mov_b64 s[46:47], 0
	s_movk_i32 s6, 0xfc0
	v_mov_b32_e32 v1, v0
	v_mov_b32_e32 v2, v0
	v_mov_b32_e32 v3, v0
	v_mov_b32_e32 v4, v0
	v_mov_b32_e32 v5, v0
	v_mov_b32_e32 v6, v0
	v_mov_b32_e32 v7, v0
	v_and_b32_e32 v9, 15, v200
	v_lshl_add_u32 v8, v9, 4, s33
	v_lshl_add_u32 v9, v9, 2, s33
	ds_read_b128 v[232:235], v8
	ds_read_b128 v[236:239], v8 offset:256
	ds_read_b128 v[240:243], v8 offset:512
	ds_read_b128 v[244:247], v8 offset:768
	ds_read_b128 v[248:251], v8 offset:1024
	ds_read_b128 v[210:213], v8 offset:1280
	ds_read_b128 v[214:217], v8 offset:1536
	ds_read_b128 v[218:221], v8 offset:1792
	ds_read_b128 v[222:225], v8 offset:2048
	ds_read_b128 v[226:229], v8 offset:2304
	ds_read_b32 v230, v9 offset:2560
	s_waitcnt vmcnt(0) lgkmcnt(0)
	v_readfirstlane_b32 s7, v200
	s_nop 3
	s_cmpk_lt_u32 s7, 0x100
	s_cbranch_scc1 .Lrw_prio_done
	s_setprio 1
.Lrw_prio_done:
	s_branch .LBB0_489
.LBB0_488:
	v_mov_b32_e32 v12, v200
	s_waitcnt lgkmcnt(0)
	s_barrier
	s_nop 0
	v_readfirstlane_b32 s12, v12
	s_bfe_u32 s7, s12, 0x10006
	v_and_b32_e32 v22, 15, v12
	s_ashr_i32 s13, s12, 3
	s_lshl_b32 s14, s7, 4
	v_bfe_u32 v23, v12, 4, 2
	v_bfi_b32 v24, -16, s13, v12
	v_or_b32_e32 v16, s14, v22
	s_and_b32 s12, s13, -16
	v_mul_lo_u32 v12, v24, s83
	v_lshlrev_b32_e32 v25, 4, v23
	v_mul_u32_u24_e32 v16, 0x50, v16
	s_add_i32 s13, 0, 0x24600
	v_add3_u32 v12, 0, v12, v25
	v_add3_u32 v16, s13, v16, v25
	ds_read_b128 v[12:15], v12 offset:58368
	ds_read_b128 v[16:19], v16
	s_add_i32 s15, 0, 0x1c400
	v_lshl_or_b32 v26, s7, 5, v22
	v_add_u32_e32 v27, s15, v25
	v_or_b32_e32 v29, 16, v26
	v_mad_u32_u24 v28, v26, s83, v27
	v_mad_u32_u24 v29, v29, s83, v27
	s_lshl_b32 s15, s7, 7
	v_add_u32_e32 v30, s15, v25
	v_add_u32_e32 v30, 0x25a00, v30
	ds_read_b128 v[114:117], v28
	ds_read_b128 v[118:121], v29
	ds_read_b128 v[122:125], v30
	ds_read_b128 v[126:129], v30 offset:64
	s_ashr_i32 s13, s12, 31
	s_lshl_b64 s[12:13], s[12:13], 1
	s_add_u32 s12, s91, s12
	s_addc_u32 s13, s92, s13
	v_mul_lo_u32 v31, v24, s76
	v_lshlrev_b32_e32 v32, 3, v23
	s_lshl_b32 s15, s7, 6
	v_add_u32_e32 v31, s85, v31
	v_add3_u32 v32, v31, v32, s15
	s_movk_i32 s16, 0x400
	s_and_b64 vcc, s[10:11], exec
	s_cselect_b32 s16, 0xfffffc00, s16
	s_cselect_b32 s17, -1, 0
	s_waitcnt lgkmcnt(4)
	v_mfma_f32_16x16x32_bf16 v[8:11], v[16:19], v[12:15], v[8:11]
	s_waitcnt lgkmcnt(3)
	v_mfma_f32_16x16x32_bf16 v[0:3], v[114:117], v[12:15], v[0:3]
	s_waitcnt lgkmcnt(2)
	v_mfma_f32_16x16x32_bf16 v[4:7], v[118:121], v[12:15], v[4:7]
	v_lshlrev_b32_e32 v16, 1, v22
	v_mov_b32_e32 v17, v38
	v_lshlrev_b32_e32 v18, 2, v23
	v_lshl_add_u64 v[16:17], s[12:13], 0, v[16:17]
	s_add_i32 s12, s46, s14
	v_add_u32_e32 v26, s12, v18
	v_or_b32_e32 v18, s14, v18
	v_sub_u32_e32 v27, s6, v18
	v_add_u32_e32 v18, 63, v27
	v_cndmask_b32_e64 v18, v26, v18, s[10:11]
	v_or_b32_e32 v18, s40, v18
	v_mov_b32_e32 v19, s41
	v_lshlrev_b64 v[20:21], 10, v[18:19]
	v_lshl_add_u64 v[20:21], v[16:17], 0, v[20:21]
	v_cvt_pk_bf16_f32 v26, v8, v8
	v_cvt_pk_bf16_f32 v27, v9, v9
	v_cvt_pk_bf16_f32 v28, v10, v10
	v_cvt_pk_bf16_f32 v29, v11, v11
	global_store_short v[20:21], v26, off
	v_lshl_add_u64 v[20:21], v[20:21], 0, s[16:17]
	global_store_short v[20:21], v27, off
	v_lshl_add_u64 v[20:21], v[20:21], 0, s[16:17]
	global_store_short v[20:21], v28, off
	v_lshl_add_u64 v[20:21], v[20:21], 0, s[16:17]
	global_store_short v[20:21], v29, off
	s_waitcnt lgkmcnt(0)
	v_pk_mul_f32 v[2:3], v[2:3], v[124:125]
	v_pk_mul_f32 v[0:1], v[0:1], v[122:123]
	v_pk_mul_f32 v[6:7], v[6:7], v[128:129]
	v_pk_mul_f32 v[4:5], v[4:5], v[126:127]
	v_cvt_pk_bf16_f32 v9, v2, v3
	v_cvt_pk_bf16_f32 v8, v0, v1
	v_cvt_pk_bf16_f32 v11, v6, v7
	v_cvt_pk_bf16_f32 v10, v4, v5
	ds_write_b64 v32, v[8:9]
	ds_write_b64 v32, v[10:11] offset:32
	s_add_u32 s46, s46, 32
	s_addc_u32 s47, s47, 0
	s_sub_i32 s6, s6, 32
	s_cmpk_lg_i32 s46, 0x1000
	s_cbranch_scc0 .LBB0_449

; __device__ __forceinline__ void rwkv_chain(LAS unsigned char* lds, int cid, const bf16_t* P0, const float* mu, const float* w0, const float* w2, const float* a0, const float* a2, ...
;     ...
;         { RW_IDS if (tid < 64) { float lw[32];
; #pragma unroll
;             for (int s = 0; s < 32; ++s) lw[s] = wS[(dir ? 31 - s : s) * 64 + tid];
; #pragma unroll
;             for (int s = 1; s < 32; ++s) lw[s] += lw[s - 1];
; #pragma unroll
;             for (int s = 0; s < 32; ++s) wS[(dir ? 31 - s : s) * 64 + tid] = lw[s]; } }
.LBB0_514:
	s_or_b64 exec, exec, s[12:13]
	v_mov_b32_e32 v8, v200
	s_waitcnt lgkmcnt(0)
	s_barrier
	s_nop 0
	v_cmp_gt_i32_e32 vcc, 64, v8
	s_and_saveexec_b64 s[12:13], vcc
	s_cbranch_execz .LBB0_516
	v_lshl_add_u32 v8, v8, 2, 0
	s_setprio 3
	s_and_b64 vcc, exec, s[10:11]
	s_cbranch_vccnz .Lrw_cum_rev
	ds_read_b32 v9, v8 offset:24576
	ds_read_b32 v17, v8 offset:24832
	ds_read_b32 v18, v8 offset:25088
	ds_read_b32 v19, v8 offset:25344
	ds_read_b32 v20, v8 offset:25600
	ds_read_b32 v21, v8 offset:25856
	ds_read_b32 v22, v8 offset:26112
	ds_read_b32 v23, v8 offset:26368
	ds_read_b32 v32, v8 offset:26624
	ds_read_b32 v33, v8 offset:26880
	ds_read_b32 v34, v8 offset:27136
	ds_read_b32 v35, v8 offset:27392
	ds_read_b32 v39, v8 offset:27648
	ds_read_b32 v114, v8 offset:27904
	ds_read_b32 v115, v8 offset:28160
	ds_read_b32 v116, v8 offset:28416
	ds_read_b32 v125, v8 offset:28672
	ds_read_b32 v126, v8 offset:28928
	ds_read_b32 v127, v8 offset:29184
	ds_read_b32 v128, v8 offset:29440
	ds_read_b32 v129, v8 offset:29696
	ds_read_b32 v130, v8 offset:29952
	ds_read_b32 v131, v8 offset:30208
	ds_read_b32 v132, v8 offset:30464
	ds_read_b32 v140, v8 offset:30720
	ds_read_b32 v141, v8 offset:30976
	ds_read_b32 v142, v8 offset:31232
	ds_read_b32 v143, v8 offset:31488
	ds_read_b32 v144, v8 offset:31744
	ds_read_b32 v145, v8 offset:32000
	ds_read_b32 v146, v8 offset:32256
	ds_read_b32 v147, v8 offset:32512
	s_waitcnt lgkmcnt(15)
	v_add_f32_e32 v17, v9, v17
	v_add_f32_e32 v18, v17, v18
	v_add_f32_e32 v19, v18, v19
	v_add_f32_e32 v20, v19, v20
	v_add_f32_e32 v21, v20, v21
	v_add_f32_e32 v22, v21, v22
	v_add_f32_e32 v23, v22, v23
	v_add_f32_e32 v32, v23, v32
	v_add_f32_e32 v33, v32, v33
	v_add_f32_e32 v34, v33, v34
	v_add_f32_e32 v35, v34, v35
	v_add_f32_e32 v39, v35, v39
	v_add_f32_e32 v114, v39, v114
	v_add_f32_e32 v115, v114, v115
	v_add_f32_e32 v116, v115, v116
	v_add_f32_e32 v125, v116, v125
	s_waitcnt lgkmcnt(14)
	v_add_f32_e32 v126, v125, v126
	s_waitcnt lgkmcnt(13)
	v_add_f32_e32 v127, v126, v127
	s_waitcnt lgkmcnt(12)
	v_add_f32_e32 v128, v127, v128
	s_waitcnt lgkmcnt(11)
	v_add_f32_e32 v129, v128, v129
	s_waitcnt lgkmcnt(10)
	v_add_f32_e32 v130, v129, v130
	s_waitcnt lgkmcnt(9)
	v_add_f32_e32 v131, v130, v131
	s_waitcnt lgkmcnt(8)
	v_add_f32_e32 v132, v131, v132
	s_waitcnt lgkmcnt(7)
	v_add_f32_e32 v140, v132, v140
	s_waitcnt lgkmcnt(6)
	v_add_f32_e32 v141, v140, v141
	s_waitcnt lgkmcnt(5)
	v_add_f32_e32 v142, v141, v142
	s_waitcnt lgkmcnt(4)
	v_add_f32_e32 v143, v142, v143
	s_waitcnt lgkmcnt(3)
	v_add_f32_e32 v144, v143, v144
	s_waitcnt lgkmcnt(2)
	v_add_f32_e32 v145, v144, v145
	s_waitcnt lgkmcnt(1)
	v_add_f32_e32 v146, v145, v146
	s_waitcnt lgkmcnt(0)
	v_add_f32_e32 v147, v146, v147
	ds_write_b32 v8, v17 offset:24832
	ds_write_b32 v8, v18 offset:25088
	ds_write_b32 v8, v19 offset:25344
	ds_write_b32 v8, v20 offset:25600
	ds_write_b32 v8, v21 offset:25856
	ds_write_b32 v8, v22 offset:26112
	ds_write_b32 v8, v23 offset:26368
	ds_write_b32 v8, v32 offset:26624
	ds_write_b32 v8, v33 offset:26880
	ds_write_b32 v8, v34 offset:27136
	ds_write_b32 v8, v35 offset:27392
	ds_write_b32 v8, v39 offset:27648
	ds_write_b32 v8, v114 offset:27904
	ds_write_b32 v8, v115 offset:28160
	ds_write_b32 v8, v116 offset:28416
	ds_write_b32 v8, v125 offset:28672
	ds_write_b32 v8, v126 offset:28928
	ds_write_b32 v8, v127 offset:29184
	ds_write_b32 v8, v128 offset:29440
	ds_write_b32 v8, v129 offset:29696
	ds_write_b32 v8, v130 offset:29952
	ds_write_b32 v8, v131 offset:30208
	ds_write_b32 v8, v132 offset:30464
	ds_write_b32 v8, v140 offset:30720
	ds_write_b32 v8, v141 offset:30976
	ds_write_b32 v8, v142 offset:31232
	ds_write_b32 v8, v143 offset:31488
	ds_write_b32 v8, v144 offset:31744
	ds_write_b32 v8, v145 offset:32000
	ds_write_b32 v8, v146 offset:32256
	ds_write_b32 v8, v147 offset:32512
	s_setprio 0
	s_branch .LBB0_516
; __device__ __forceinline__ void rwkv_chain(LAS unsigned char* lds, int cid, const bf16_t* P0, const float* mu, const float* w0, const float* w2, const float* a0, const float* a2, ...
;     ...
;         { RW_IDS if (tid < 64) { float lw[32];
; #pragma unroll
;             for (int s = 0; s < 32; ++s) lw[s] = wS[(dir ? 31 - s : s) * 64 + tid];
; #pragma unroll
;             for (int s = 1; s < 32; ++s) lw[s] += lw[s - 1];
; #pragma unroll
;             for (int s = 0; s < 32; ++s) wS[(dir ? 31 - s : s) * 64 + tid] = lw[s]; } }
.Lrw_cum_rev:
	ds_read_b32 v9, v8 offset:32512
	ds_read_b32 v17, v8 offset:32256
	ds_read_b32 v18, v8 offset:32000
	ds_read_b32 v19, v8 offset:31744
	ds_read_b32 v20, v8 offset:31488
	ds_read_b32 v21, v8 offset:31232
	ds_read_b32 v22, v8 offset:30976
	ds_read_b32 v23, v8 offset:30720
	ds_read_b32 v32, v8 offset:30464
	ds_read_b32 v33, v8 offset:30208
	ds_read_b32 v34, v8 offset:29952
	ds_read_b32 v35, v8 offset:29696
	ds_read_b32 v39, v8 offset:29440
	ds_read_b32 v114, v8 offset:29184
	ds_read_b32 v115, v8 offset:28928
	ds_read_b32 v116, v8 offset:28672
	ds_read_b32 v125, v8 offset:28416
	ds_read_b32 v126, v8 offset:28160
	ds_read_b32 v127, v8 offset:27904
	ds_read_b32 v128, v8 offset:27648
	ds_read_b32 v129, v8 offset:27392
	ds_read_b32 v130, v8 offset:27136
	ds_read_b32 v131, v8 offset:26880
	ds_read_b32 v132, v8 offset:26624
	ds_read_b32 v140, v8 offset:26368
	ds_read_b32 v141, v8 offset:26112
	ds_read_b32 v142, v8 offset:25856
	ds_read_b32 v143, v8 offset:25600
	ds_read_b32 v144, v8 offset:25344
	ds_read_b32 v145, v8 offset:25088
	ds_read_b32 v146, v8 offset:24832
	ds_read_b32 v147, v8 offset:24576
	s_waitcnt lgkmcnt(15)
	v_add_f32_e32 v17, v9, v17
	v_add_f32_e32 v18, v17, v18
	v_add_f32_e32 v19, v18, v19
	v_add_f32_e32 v20, v19, v20
	v_add_f32_e32 v21, v20, v21
	v_add_f32_e32 v22, v21, v22
	v_add_f32_e32 v23, v22, v23
	v_add_f32_e32 v32, v23, v32
	v_add_f32_e32 v33, v32, v33
	v_add_f32_e32 v34, v33, v34
	v_add_f32_e32 v35, v34, v35
	v_add_f32_e32 v39, v35, v39
	v_add_f32_e32 v114, v39, v114
	v_add_f32_e32 v115, v114, v115
	v_add_f32_e32 v116, v115, v116
	v_add_f32_e32 v125, v116, v125
	s_waitcnt lgkmcnt(14)
	v_add_f32_e32 v126, v125, v126
	s_waitcnt lgkmcnt(13)
	v_add_f32_e32 v127, v126, v127
	s_waitcnt lgkmcnt(12)
	v_add_f32_e32 v128, v127, v128
	s_waitcnt lgkmcnt(11)
	v_add_f32_e32 v129, v128, v129
	s_waitcnt lgkmcnt(10)
	v_add_f32_e32 v130, v129, v130
	s_waitcnt lgkmcnt(9)
	v_add_f32_e32 v131, v130, v131
	s_waitcnt lgkmcnt(8)
	v_add_f32_e32 v132, v131, v132
	s_waitcnt lgkmcnt(7)
	v_add_f32_e32 v140, v132, v140
	s_waitcnt lgkmcnt(6)
	v_add_f32_e32 v141, v140, v141
	s_waitcnt lgkmcnt(5)
	v_add_f32_e32 v142, v141, v142
	s_waitcnt lgkmcnt(4)
	v_add_f32_e32 v143, v142, v143
	s_waitcnt lgkmcnt(3)
	v_add_f32_e32 v144, v143, v144
	s_waitcnt lgkmcnt(2)
	v_add_f32_e32 v145, v144, v145
	s_waitcnt lgkmcnt(1)
	v_add_f32_e32 v146, v145, v146
	s_waitcnt lgkmcnt(0)
	v_add_f32_e32 v147, v146, v147
	ds_write_b32 v8, v17 offset:32256
	ds_write_b32 v8, v18 offset:32000
	ds_write_b32 v8, v19 offset:31744
	ds_write_b32 v8, v20 offset:31488
	ds_write_b32 v8, v21 offset:31232
	ds_write_b32 v8, v22 offset:30976
	ds_write_b32 v8, v23 offset:30720
	ds_write_b32 v8, v32 offset:30464
	ds_write_b32 v8, v33 offset:30208
	ds_write_b32 v8, v34 offset:29952
	ds_write_b32 v8, v35 offset:29696
	ds_write_b32 v8, v39 offset:29440
	ds_write_b32 v8, v114 offset:29184
	ds_write_b32 v8, v115 offset:28928
	ds_write_b32 v8, v116 offset:28672
	ds_write_b32 v8, v125 offset:28416
	ds_write_b32 v8, v126 offset:28160
	ds_write_b32 v8, v127 offset:27904
	ds_write_b32 v8, v128 offset:27648
	ds_write_b32 v8, v129 offset:27392
	ds_write_b32 v8, v130 offset:27136
	ds_write_b32 v8, v131 offset:26880
	ds_write_b32 v8, v132 offset:26624
	ds_write_b32 v8, v140 offset:26368
	ds_write_b32 v8, v141 offset:26112
	ds_write_b32 v8, v142 offset:25856
	ds_write_b32 v8, v143 offset:25600
	ds_write_b32 v8, v144 offset:25344
	ds_write_b32 v8, v145 offset:25088
	ds_write_b32 v8, v146 offset:24832
	ds_write_b32 v8, v147 offset:24576
	s_setprio 0
